# aligned the per-XCD unit chunks of the GEMM phases to whole row panels (32 panels per XCD, tail units kept separate) so consecutive phases read on the same XCD what it just wrote; MLP down-proj runs i
# speedup vs baseline: 1.0112x; 1.0045x over previous
;     __device__ bool next(int i, Unit& u) const {
;         const long L = (long)i * G + c; if (L >= nwg) return false;
;         int wgid = (int)L; { const int q = nwg / NXCD, r = nwg % NXCD, xcd = wgid % NXCD, off = wgid / NXCD; wgid = (xcd < r ? xcd * (q + 1) : r * (q + 1) + (xcd - r) * q) + off; }
;         const int nig = WGM * nN, gid = wgid / nig, fm = gid * WGM, gsz = (nM - fm) < WGM ? (nM - fm) : WGM;
;         u.pm = fm + ((wgid % nig) % gsz); u.pn = (wgid % nig) / gsz; u.ko = 0; return true;
.LBB0_302:
	s_mov_b32 s8, s88
	s_mov_b64 s[4:5], s[74:75]
	s_mov_b32 s9, s83
	s_mov_b32 s0, s13
	v_mov_b32_e32 v8, v242
	s_cmpk_lt_i32 s9, 0x820
	s_cselect_b64 s[6:7], -1, 0
	s_cmpk_gt_i32 s9, 0x81f
	v_readfirstlane_b32 s18, v8
	s_cbranch_scc1 .LBB0_304
	s_ashr_i32 s1, s9, 31
	s_lshr_b32 s1, s1, 29
	s_add_i32 s1, s9, s1
	s_ashr_i32 s2, s1, 3
	s_and_b32 s1, s1, -8
	s_sub_i32 s1, s9, s1
	s_cmp_lt_i32 s1, 0
	s_movk_i32 s3, 0x100
	s_cselect_b32 s3, s3, 0x100
	s_mul_i32 s1, s1, s3
	s_add_i32 s1, s1, s2
	s_ashr_i32 s2, s1, 31
	s_lshr_b32 s2, s2, 26
	s_add_i32 s2, s1, s2
	s_ashr_i32 s3, s2, 6
	s_lshl_b32 s10, s3, 3
	s_sub_i32 s3, 0x104, s10
	s_min_u32 s11, s3, 8
	s_andn2_b32 s2, s2, 63
	s_sub_i32 s1, s1, s2
	v_cvt_f32_ubyte0_e32 v1, s11
	v_cvt_f32_i32_e32 v0, s1
	v_rcp_iflag_f32_e32 v2, v1
	s_ashr_i32 s2, s1, 30
	s_or_b32 s12, s2, 1
	v_mul_f32_e32 v2, v0, v2
	v_trunc_f32_e32 v2, v2
	v_fma_f32 v0, -v2, v1, v0
	v_cvt_i32_f32_e32 v2, v2
	v_cmp_ge_f32_e64 s[2:3], |v0|, v1
	s_and_b64 s[2:3], s[2:3], exec
	s_cselect_b32 s2, s12, 0
	v_readfirstlane_b32 s3, v2
	s_add_i32 s3, s3, s2
	s_sext_i32_i8 s2, s3
	s_mul_i32 s3, s3, s11
	s_sub_i32 s1, s1, s3
	s_sext_i32_i8 s1, s1
	s_add_i32 s16, s10, s1

;     __device__ bool next(int i, Unit& u) const {
;         const long L = (long)i * G + c; if (L >= nwg) return false;
;         int wgid = (int)L; { const int q = nwg / NXCD, r = nwg % NXCD, xcd = wgid % NXCD, off = wgid / NXCD; wgid = (xcd < r ? xcd * (q + 1) : r * (q + 1) + (xcd - r) * q) + off; }
;         const int nig = WGM * nN, gid = wgid / nig, fm = gid * WGM, gsz = (nM - fm) < WGM ? (nM - fm) : WGM;
;         u.pm = fm + ((wgid % nig) % gsz); u.pn = (wgid % nig) / gsz; u.ko = 0; return true;
.LBB0_310:
	s_add_i32 s33, s33, 1
	s_mul_i32 s0, s33, s18
	s_mul_hi_u32 s1, s33, s8
	s_add_i32 s1, s1, s0
	s_mul_i32 s0, s33, s8
	s_add_u32 s4, s0, s9
	s_addc_u32 s5, s1, s19
	v_mov_b64_e32 v[0:1], 0x820
	v_cmp_lt_i64_e64 s[0:1], s[4:5], v[0:1]
	v_mov_b64_e32 v[0:1], 0x81f
	v_cmp_gt_i64_e32 vcc, s[4:5], v[0:1]
	s_cbranch_vccnz .LBB0_312
	s_ashr_i32 s3, s4, 31
	s_lshr_b32 s3, s3, 29
	s_add_i32 s3, s4, s3
	s_ashr_i32 s5, s3, 3
	s_and_b32 s3, s3, -8
	s_sub_i32 s3, s4, s3
	s_cmp_lt_i32 s3, 0
	s_movk_i32 s4, 0x100
	s_cselect_b32 s4, s4, 0x100
	s_mul_i32 s3, s3, s4
	s_add_i32 s3, s3, s5
	s_mul_i32 s4, s33, s8
	s_add_i32 s4, s4, s9
	s_cmpk_lt_i32 s4, 0x800
	s_cselect_b32 s3, s3, s4
	s_ashr_i32 s4, s3, 31
	s_lshr_b32 s4, s4, 26
	s_add_i32 s4, s3, s4
	s_ashr_i32 s5, s4, 6
	s_lshl_b32 s5, s5, 3
	s_sub_i32 s6, 0x104, s5
	s_min_i32 s6, s6, 8
	s_abs_i32 s7, s6
	v_cvt_f32_u32_e32 v0, s7
	s_sub_i32 s20, 0, s7
	s_andn2_b32 s4, s4, 63
	s_sub_i32 s3, s3, s4
	v_rcp_iflag_f32_e32 v0, v0
	s_abs_i32 s4, s3
	s_xor_b32 s17, s3, s6
	s_ashr_i32 s17, s17, 31
	v_mul_f32_e32 v0, 0x4f7ffffe, v0
	v_cvt_u32_f32_e32 v0, v0
	s_nop 0
	v_readfirstlane_b32 s21, v0
	s_mul_i32 s20, s20, s21
	s_mul_hi_u32 s20, s21, s20
	s_add_i32 s21, s21, s20
	s_mul_hi_u32 s20, s4, s21
	s_mul_i32 s21, s20, s7
	s_sub_i32 s4, s4, s21
	s_add_i32 s22, s20, 1
	s_sub_i32 s21, s4, s7
	s_cmp_ge_u32 s4, s7
	s_cselect_b32 s20, s22, s20
	s_cselect_b32 s4, s21, s4
	s_add_i32 s21, s20, 1
	s_cmp_ge_u32 s4, s7
	s_cselect_b32 s4, s21, s20
	s_xor_b32 s4, s4, s17
	s_sub_i32 s92, s4, s17
	s_mul_i32 s4, s92, s6
	s_sub_i32 s3, s3, s4
	s_add_i32 s94, s5, s3

;     __device__ bool next(int i, Unit& u) const {
;         const long L = (long)i * G + c; if (L >= nwg) return false;
;         int wgid = (int)L; { const int q = nwg / NXCD, r = nwg % NXCD, xcd = wgid % NXCD, off = wgid / NXCD; wgid = (xcd < r ? xcd * (q + 1) : r * (q + 1) + (xcd - r) * q) + off; }
;         const int nig = WGM * nN, gid = wgid / nig, fm = gid * WGM, gsz = (nM - fm) < WGM ? (nM - fm) : WGM;
;         u.pm = fm + ((wgid % nig) % gsz); u.pn = (wgid % nig) / gsz; u.ko = 0; return true;
.LBB0_662:
	s_or_b64 exec, exec, s[0:1]
	s_mov_b32 s7, s14
	s_mov_b32 s62, s90
	s_mov_b64 s[0:1], s[74:75]
	s_mov_b32 s64, s83
	s_waitcnt lgkmcnt(0)
	s_barrier
	v_mov_b32_e32 v8, v242
	s_cmpk_lt_i32 s64, 0x410
	s_cselect_b64 s[2:3], -1, 0
	s_cmpk_gt_i32 s64, 0x40f
	v_readfirstlane_b32 s6, v8
	s_cbranch_scc1 .LBB0_664
	s_ashr_i32 s4, s64, 31
	s_lshr_b32 s4, s4, 29
	s_add_i32 s4, s64, s4
	s_ashr_i32 s5, s4, 3
	s_and_b32 s4, s4, -8
	s_sub_i32 s4, s64, s4
	s_cmp_lt_i32 s4, 0
	s_movk_i32 s8, 0x80
	s_cselect_b32 s8, s8, 0x80
	s_mul_i32 s4, s4, s8
	s_add_i32 s4, s4, s5
	s_ashr_i32 s5, s4, 31
	s_lshr_b32 s5, s5, 27
	s_add_i32 s5, s4, s5
	s_ashr_i32 s8, s5, 5
	s_lshl_b32 s8, s8, 3
	s_sub_i32 s9, 0x104, s8
	s_min_u32 s9, s9, 8
	s_andn2_b32 s5, s5, 31
	s_sub_i32 s10, s4, s5
	v_cvt_f32_ubyte0_e32 v1, s9
	v_cvt_f32_i32_e32 v0, s10
	v_rcp_iflag_f32_e32 v2, v1
	s_ashr_i32 s4, s10, 30
	s_or_b32 s11, s4, 1
	v_mul_f32_e32 v2, v0, v2
	v_trunc_f32_e32 v2, v2
	v_fma_f32 v0, -v2, v1, v0
	v_cvt_i32_f32_e32 v2, v2
	v_cmp_ge_f32_e64 s[4:5], |v0|, v1
	s_and_b64 s[4:5], s[4:5], exec
	s_cselect_b32 s4, s11, 0
	v_readfirstlane_b32 s5, v2
	s_add_i32 s5, s5, s4
	s_sext_i32_i8 s4, s5
	s_mul_i32 s5, s5, s9
	s_sub_i32 s5, s10, s5
	s_sext_i32_i8 s5, s5
	s_add_i32 s16, s8, s5

;     __device__ bool next(int i, Unit& u) const {
;         const long L = (long)i * G + c; if (L >= nwg) return false;
;         int wgid = (int)L; { const int q = nwg / NXCD, r = nwg % NXCD, xcd = wgid % NXCD, off = wgid / NXCD; wgid = (xcd < r ? xcd * (q + 1) : r * (q + 1) + (xcd - r) * q) + off; }
;         const int nig = WGM * nN, gid = wgid / nig, fm = gid * WGM, gsz = (nM - fm) < WGM ? (nM - fm) : WGM;
;         u.pm = fm + ((wgid % nig) % gsz); u.pn = (wgid % nig) / gsz; u.ko = 0; return true;
.LBB0_670:
	s_add_i32 s77, s77, 1
	s_mul_i32 s2, s77, s8
	s_mul_hi_u32 s3, s77, s62
	s_add_i32 s3, s3, s2
	s_mul_i32 s2, s77, s62
	s_add_u32 s6, s2, s64
	s_addc_u32 s7, s3, s9
	v_cmp_gt_i64_e32 vcc, s[6:7], v[204:205]
	v_cmp_lt_i64_e64 s[2:3], s[6:7], v[202:203]
	s_cbranch_vccnz .LBB0_672
	s_ashr_i32 s5, s6, 31
	s_lshr_b32 s5, s5, 29
	s_add_i32 s5, s6, s5
	s_ashr_i32 s7, s5, 3
	s_and_b32 s5, s5, -8
	s_sub_i32 s5, s6, s5
	s_cmp_lt_i32 s5, 0
	s_movk_i32 s6, 0x80
	s_cselect_b32 s6, s6, 0x80
	s_mul_i32 s5, s5, s6
	s_add_i32 s5, s5, s7
	s_mul_i32 s6, s77, s62
	s_add_i32 s6, s6, s64
	s_cmpk_lt_i32 s6, 0x400
	s_cselect_b32 s5, s5, s6
	s_ashr_i32 s6, s5, 31
	s_lshr_b32 s6, s6, 27
	s_add_i32 s6, s5, s6
	s_ashr_i32 s7, s6, 5
	s_lshl_b32 s7, s7, 3
	s_sub_i32 s12, 0x104, s7
	s_min_i32 s12, s12, 8
	s_abs_i32 s13, s12
	v_cvt_f32_u32_e32 v0, s13
	s_sub_i32 s15, 0, s13
	s_andn2_b32 s6, s6, 31
	s_sub_i32 s5, s5, s6
	v_rcp_iflag_f32_e32 v0, v0
	s_abs_i32 s6, s5
	s_xor_b32 s14, s5, s12
	s_ashr_i32 s14, s14, 31
	v_mul_f32_e32 v0, 0x4f7ffffe, v0
	v_cvt_u32_f32_e32 v0, v0
	s_nop 0
	v_readfirstlane_b32 s18, v0
	s_mul_i32 s15, s15, s18
	s_mul_hi_u32 s15, s18, s15
	s_add_i32 s18, s18, s15
	s_mul_hi_u32 s15, s6, s18
	s_mul_i32 s18, s15, s13
	s_sub_i32 s6, s6, s18
	s_add_i32 s19, s15, 1
	s_sub_i32 s18, s6, s13
	s_cmp_ge_u32 s6, s13
	s_cselect_b32 s15, s19, s15
	s_cselect_b32 s6, s18, s6
	s_add_i32 s18, s15, 1
	s_cmp_ge_u32 s6, s13
	s_cselect_b32 s6, s18, s15
	s_xor_b32 s6, s6, s14
	s_sub_i32 s86, s6, s14
	s_mul_i32 s6, s86, s12
	s_sub_i32 s5, s5, s6
	s_add_i32 s88, s7, s5

;     __device__ bool next(int i, Unit& u) const {
;         const long L = (long)i * G + c; if (L >= nwg) return false;
;         int wgid = (int)L; { const int q = nwg / NXCD, r = nwg % NXCD, xcd = wgid % NXCD, off = wgid / NXCD; wgid = (xcd < r ? xcd * (q + 1) : r * (q + 1) + (xcd - r) * q) + off; }
;         const int nig = WGM * nN, gid = wgid / nig, fm = gid * WGM, gsz = (nM - fm) < WGM ? (nM - fm) : WGM;
; template <class Epi, bool SP2, class Sched>
; __device__ __forceinline__ void gemm_phase(LAS unsigned char* lds, const Gemm g, const Sched& S, const Epi& E) {
;     ...
;     const int wid = __builtin_amdgcn_readfirstlane(tid >> 6), lane = tid & 63, wr = wid >> 2, wc = wid & 3, fr = lane & 15, fq = lane >> 4;
;     const int K = g.K, nt = K / BK;
;     unsigned voffA[2], voffB[2];
; #pragma unroll
;     for (int i = 0; i < 2; ++i) { int R, C; stage_rc(tid * 16 + i * 8192, R, C); const int Rb = Epi::PERM ? ((R & ~31) + perm32(R & 31)) : R;
;         voffA[i] = (unsigned)(R * g.lda + C) * 2u; voffB[i] = (unsigned)(Rb * g.ldb + C) * 2u; }
;     const size_t kstep = (size_t)(BK * 2);
;     const size_t hstep = (size_t)HALF * g.lda * 2, hstepB = (size_t)HALF * g.ldb * 2;
;     const size_t tstep = 2 * hstep, tstepB = 2 * hstepB;
;     const unsigned ldsw = (unsigned)wid * 1024u;
;     const int aoff = lds_byte(wr * 64 + fr, fq * 8), boff = lds_byte(wc * 32 + fr, fq * 8);
;     ...
;     Unit cur, nxt; int ui = 0;
;     if (!S.next(0, cur)) return;
;     f32x4 acc[2][2][4][2];
; #pragma unroll
;     for (int a = 0; a < 2; ++a)
; #pragma unroll
;         for (int b = 0; b < 2; ++b)
; #pragma unroll
;             for (int m = 0; m < 4; ++m)
; #pragma unroll
;                 for (int n = 0; n < 2; ++n) acc[a][b][m][n] = (f32x4){0.f, 0.f, 0.f, 0.f};
;     bf16x8 At[4][2], B0[2][2], B1[2][2];
;     const char* cA = (const char*)g.A + (size_t)cur.pm * tstep + cur.ko; const char* cB = (const char*)g.Bt + (size_t)cur.pn * tstepB + cur.ko;
;     if constexpr (SP2) {
;         PG8_STAGE(PG8_SB(0, 0), cB, voffB); PG8_STAGE(PG8_SB(0, 1), cB + hstepB, voffB); PG8_STAGE(PG8_SA(0, 0), cA, voffA); PG8_STAGE(PG8_SA(0, 1), cA + hstep, voffA);
;         if (wr == 1) PG8_BAR;
;         PG8_WAIT_V(2); PG8_BAR;
;         PG8_STAGE(PG8_SB(1, 0), cB + kstep, voffB); PG8_STAGE(PG8_SA(1, 0), cA + kstep, voffA); PG8_STAGE(PG8_SB(1, 1), cB + hstepB + kstep, voffB);
;         PG8_WAIT_V(6); PG8_BAR;
.LBB0_774:
	s_or_b64 exec, exec, s[0:1]
	s_mov_b64 s[0:1], s[74:75]
	s_mov_b32 s8, s83
	s_mov_b32 s18, s14
	s_mov_b32 s9, s90
	v_mov_b32_e32 v14, v242
	s_waitcnt lgkmcnt(0)
	s_barrier
	s_cmpk_gt_i32 s8, 0x40f
	v_readfirstlane_b32 s5, v14
	s_cbranch_scc1 .LBB0_790
	v_lshlrev_b32_e32 v0, 4, v14
	v_add_u32_e32 v1, 0x2000, v0
	v_ashrrev_i32_e32 v2, 31, v1
	v_lshrrev_b32_e32 v2, 22, v2
	v_add_u32_e32 v2, v1, v2
	v_ashrrev_i32_e32 v8, 10, v2
	v_mul_i32_i24_e32 v2, 0x400, v8
	v_sub_u32_e32 v1, v1, v2
	v_lshrrev_b32_e32 v2, 4, v1
	s_mul_i32 s3, s18, 0x1f00000
	v_bitop3_b32 v1, v2, v1, 32 bitop3:0x6c
	s_mul_hi_i32 s2, s18, 0x1f00000
	s_add_u32 s3, s0, s3
	v_ashrrev_i32_e32 v2, 31, v1
	s_addc_u32 s2, s1, s2
	v_lshrrev_b32_e32 v2, 26, v2
	s_add_u32 s62, s0, 0x4200000
	v_add_u32_e32 v2, v1, v2
	v_lshlrev_b32_e32 v3, 3, v8
	s_addc_u32 s64, s1, 0
	v_ashrrev_i32_e32 v9, 6, v2
	v_and_b32_e32 v3, -16, v3
	s_add_u32 s65, s3, 0xa80000
	v_add_u32_e32 v3, v9, v3
	s_addc_u32 s68, s2, 0
	v_and_b32_e32 v4, 3, v9
	s_mov_b32 s2, 0x1fffe0
	v_lshrrev_b32_e32 v5, 2, v3
	v_lshlrev_b32_e32 v6, 1, v3
	v_and_b32_e32 v2, 0xc0, v2
	v_and_or_b32 v4, v3, s2, v4
	v_and_b32_e32 v5, 4, v5
	v_and_b32_e32 v6, 24, v6
	v_sub_u32_e32 v1, v1, v2
	v_or3_b32 v4, v4, v5, v6
	v_lshlrev_b32_e32 v5, 5, v8
	v_ashrrev_i16_sdwa v1, v244, sext(v1) dst_sel:DWORD dst_unused:UNUSED_PAD src0_sel:DWORD src1_sel:BYTE_0
	v_and_b32_e32 v5, 32, v5
	v_bfe_i32 v10, v1, 0, 16
	v_add_lshl_u32 v1, v5, v10, 1
	v_lshl_add_u32 v130, v4, 11, v1
	v_lshl_add_u32 v132, v3, 11, v1
	v_bfe_i32 v1, v14, 27, 1
	v_lshrrev_b32_e32 v1, 22, v1
	v_add_u32_e32 v1, v0, v1
	v_and_b32_e32 v1, 0xfffffc00, v1
	v_sub_u32_e32 v0, v0, v1
	v_lshrrev_b32_e32 v1, 4, v0
	v_ashrrev_i32_e32 v2, 31, v14
	v_bitop3_b32 v0, v1, v0, 32 bitop3:0x6c
	v_lshrrev_b32_e32 v2, 26, v2
	v_ashrrev_i32_e32 v1, 31, v0
	v_add_u32_e32 v2, v14, v2
	v_lshrrev_b32_e32 v1, 26, v1
	v_ashrrev_i32_e32 v12, 6, v2
	v_add_u32_e32 v1, v0, v1
	v_lshlrev_b32_e32 v2, 3, v12
	v_ashrrev_i32_e32 v11, 6, v1
	v_and_b32_e32 v2, -16, v2
	v_add_u32_e32 v2, v11, v2
	v_and_b32_e32 v3, 3, v11
	s_ashr_i32 s72, s8, 31
	v_and_or_b32 v3, v2, s2, v3
	s_lshr_b32 s2, s72, 29
	s_add_i32 s2, s8, s2
	s_ashr_i32 s6, s5, 6
	s_ashr_i32 s3, s2, 3
	s_and_b32 s2, s2, -8
	s_ashr_i32 s7, s5, 8
	s_lshl_b32 s69, s6, 10
	s_sub_i32 s2, s8, s2
	s_cmp_lt_i32 s2, 0
	s_movk_i32 s4, 0x80
	s_cselect_b32 s4, s4, 0x80
	s_mul_i32 s2, s2, s4
	s_add_i32 s2, s2, s3
	s_ashr_i32 s3, s2, 31
	s_lshr_b32 s3, s3, 27
	v_lshrrev_b32_e32 v4, 2, v2
	v_lshlrev_b32_e32 v5, 1, v2
	v_and_b32_e32 v1, 0xc0, v1
	s_add_i32 s3, s2, s3
	v_and_b32_e32 v4, 4, v4
	v_and_b32_e32 v5, 24, v5
	v_sub_u32_e32 v0, v0, v1
	s_ashr_i32 s4, s3, 5
	v_or3_b32 v3, v3, v4, v5
	v_lshlrev_b32_e32 v4, 5, v12
	v_ashrrev_i16_sdwa v0, v244, sext(v0) dst_sel:DWORD dst_unused:UNUSED_PAD src0_sel:DWORD src1_sel:BYTE_0
	s_lshl_b32 s10, s4, 3
	v_and_b32_e32 v4, 32, v4
	v_bfe_i32 v13, v0, 0, 16
	s_sub_i32 s4, 0x104, s10
	v_add_lshl_u32 v0, v4, v13, 1
	s_min_u32 s11, s4, 8
	s_andn2_b32 s3, s3, 31
	v_lshl_add_u32 v64, v3, 11, v0
	s_sub_i32 s12, s2, s3
	v_cvt_f32_ubyte0_e32 v3, s11
	v_cvt_f32_i32_e32 v1, s12
	v_rcp_iflag_f32_e32 v4, v3
	v_lshl_add_u32 v134, v2, 11, v0
	s_ashr_i32 s2, s12, 30
	s_or_b32 s4, s2, 1
	v_mul_f32_e32 v0, v1, v4
	v_trunc_f32_e32 v0, v0
	v_fma_f32 v1, -v0, v3, v1
	v_cvt_i32_f32_e32 v0, v0
	v_cmp_ge_f32_e64 s[2:3], |v1|, v3
	s_and_b64 s[2:3], s[2:3], exec
	s_cselect_b32 s2, s4, 0
	v_readfirstlane_b32 s3, v0
	s_add_i32 s4, s3, s2
	s_mul_i32 s2, s4, s11
	s_sub_i32 s2, s12, s2
	s_sext_i32_i8 s2, s2
	s_add_i32 s16, s10, s2
	s_ashr_i32 s17, s16, 31
	s_bfe_i64 s[10:11], s[4:5], 0x80000
	s_lshl_b64 s[2:3], s[16:17], 19
	s_lshl_b64 s[10:11], s[10:11], 19
	s_add_u32 s10, s65, s10
	s_addc_u32 s11, s68, s11
	s_add_i32 s12, s69, 0
	s_add_i32 m0, s12, 0x10000
	v_mov_b32_e32 v131, v65
	global_load_lds_dwordx4 v64, s[10:11]
	s_add_i32 m0, s12, 0x12000
	s_add_u32 s14, s10, 0x40000
	global_load_lds_dwordx4 v130, s[10:11]
	s_addc_u32 s15, s11, 0
	s_add_i32 m0, s12, 0x14000
	v_mov_b32_e32 v135, v65
	global_load_lds_dwordx4 v64, s[14:15]
	s_add_i32 m0, s12, 0x16000
	s_add_u32 s88, s62, s2
	s_addc_u32 s89, s64, s3
	s_add_i32 s13, s12, 0x2000
	global_load_lds_dwordx4 v130, s[14:15]
	s_mov_b32 m0, s12
	s_add_u32 s2, s88, 0x40000
	global_load_lds_dwordx4 v134, s[88:89]
	s_mov_b32 m0, s13
	s_addc_u32 s3, s89, 0
	s_add_i32 s14, s12, 0x4000
	global_load_lds_dwordx4 v132, s[88:89]
	s_mov_b32 m0, s14
	s_add_i32 s15, s12, 0x6000
	global_load_lds_dwordx4 v134, s[2:3]
	s_mov_b32 m0, s15
	v_mov_b32_e32 v133, v65
	global_load_lds_dwordx4 v132, s[2:3]
	s_cmp_eq_u32 s7, 1
	v_lshl_add_u64 v[6:7], s[10:11], 0, v[64:65]
	v_lshl_add_u64 v[4:5], s[10:11], 0, v[130:131]
	v_lshl_add_u64 v[0:1], s[88:89], 0, v[134:135]
	s_cselect_b64 s[2:3], -1, 0
	s_cmp_lg_u32 s7, 1
	v_lshl_add_u64 v[2:3], s[88:89], 0, v[132:133]
	s_cbranch_scc1 .LBB0_777
	s_barrier

;     __device__ bool next(int i, Unit& u) const {
;         const long L = (long)i * G + c; if (L >= nwg) return false;
;         int wgid = (int)L; { const int q = nwg / NXCD, r = nwg % NXCD, xcd = wgid % NXCD, off = wgid / NXCD; wgid = (xcd < r ? xcd * (q + 1) : r * (q + 1) + (xcd - r) * q) + off; }
;         const int nig = WGM * nN, gid = wgid / nig, fm = gid * WGM, gsz = (nM - fm) < WGM ? (nM - fm) : WGM;
;         u.pm = fm + ((wgid % nig) % gsz); u.pn = (wgid % nig) / gsz; u.ko = 0; return true;
.LBB0_780:
	s_add_i32 s33, s33, 1
	s_mul_i32 s0, s33, s19
	s_mul_hi_u32 s1, s33, s9
	s_add_i32 s1, s1, s0
	s_mul_i32 s0, s33, s9
	s_add_u32 s6, s0, s8
	s_addc_u32 s7, s1, s72
	v_cmp_gt_i64_e32 vcc, s[6:7], v[204:205]
	v_cmp_lt_i64_e64 s[0:1], s[6:7], v[202:203]
	s_cbranch_vccnz .LBB0_782
	s_ashr_i32 s7, s6, 31
	s_lshr_b32 s7, s7, 29
	s_add_i32 s7, s6, s7
	s_ashr_i32 s20, s7, 3
	s_and_b32 s7, s7, -8
	s_sub_i32 s6, s6, s7
	s_cmp_lt_i32 s6, 0
	s_movk_i32 s7, 0x80
	s_cselect_b32 s7, s7, 0x80
	s_mul_i32 s6, s6, s7
	s_add_i32 s6, s6, s20
	s_mul_i32 s7, s33, s9
	s_add_i32 s7, s7, s8
	s_cmpk_lt_i32 s7, 0x400
	s_cselect_b32 s6, s6, s7
	s_ashr_i32 s7, s6, 31
	s_lshr_b32 s7, s7, 27
	s_add_i32 s7, s6, s7
	s_ashr_i32 s20, s7, 5
	s_lshl_b32 s20, s20, 3
	s_sub_i32 s21, 0x104, s20
	s_min_i32 s21, s21, 8
	s_abs_i32 s22, s21
	v_cvt_f32_u32_e32 v0, s22
	s_sub_i32 s24, 0, s22
	s_andn2_b32 s7, s7, 31
	s_sub_i32 s6, s6, s7
	v_rcp_iflag_f32_e32 v0, v0
	s_abs_i32 s7, s6
	s_xor_b32 s23, s6, s21
	s_ashr_i32 s23, s23, 31
	v_mul_f32_e32 v0, 0x4f7ffffe, v0
	v_cvt_u32_f32_e32 v0, v0
	s_nop 0
	v_readfirstlane_b32 s25, v0
	s_mul_i32 s24, s24, s25
	s_mul_hi_u32 s24, s25, s24
	s_add_i32 s25, s25, s24
	s_mul_hi_u32 s24, s7, s25
	s_mul_i32 s25, s24, s22
	s_sub_i32 s7, s7, s25
	s_add_i32 s58, s24, 1
	s_sub_i32 s25, s7, s22
	s_cmp_ge_u32 s7, s22
	s_cselect_b32 s24, s58, s24
	s_cselect_b32 s7, s25, s7
	s_add_i32 s25, s24, 1
	s_cmp_ge_u32 s7, s22
	s_cselect_b32 s7, s25, s24
	s_xor_b32 s7, s7, s23
	s_sub_i32 s58, s7, s23
	s_mul_i32 s7, s58, s21
	s_sub_i32 s6, s6, s7
	s_mov_b32 s25, 0x40000
	s_add_i32 s60, s20, s6

;     __device__ bool next(int i, Unit& u) const {
;         const long L = (long)i * G + c; if (L >= nwg) return false;
;         int wgid = (int)L; { const int q = nwg / NXCD, r = nwg % NXCD, xcd = wgid % NXCD, off = wgid / NXCD; wgid = (xcd < r ? xcd * (q + 1) : r * (q + 1) + (xcd - r) * q) + off; }
;         const int nig = WGM * nN, gid = wgid / nig, fm = gid * WGM, gsz = (nM - fm) < WGM ? (nM - fm) : WGM;
;         u.pm = fm + ((wgid % nig) % gsz); u.pn = (wgid % nig) / gsz; u.ko = 0; return true;
.LBB0_944:
	s_or_b64 exec, exec, s[0:1]
	s_mov_b32 s8, s90
	s_mov_b64 s[0:1], s[74:75]
	s_mov_b32 s9, s83
	s_mov_b32 s5, s14
	s_waitcnt lgkmcnt(0)
	s_barrier
	v_mov_b32_e32 v8, v242
	s_cmpk_lt_i32 s9, 0x410
	s_cselect_b64 s[2:3], -1, 0
	s_cmpk_gt_i32 s9, 0x40f
	v_readfirstlane_b32 s4, v8
	s_cbranch_scc1 .LBB0_946
	s_ashr_i32 s6, s9, 31
	s_lshr_b32 s6, s6, 29
	s_add_i32 s6, s9, s6
	s_ashr_i32 s7, s6, 3
	s_and_b32 s6, s6, -8
	s_sub_i32 s6, s9, s6
	s_cmp_lt_i32 s6, 0
	s_movk_i32 s10, 0x80
	s_cselect_b32 s10, s10, 0x80
	s_mul_i32 s6, s6, s10
	s_add_i32 s6, s6, s7
	s_ashr_i32 s7, s6, 31
	s_lshr_b32 s7, s7, 27
	s_add_i32 s7, s6, s7
	s_ashr_i32 s10, s7, 5
	s_lshl_b32 s10, s10, 3
	s_sub_i32 s11, 0x104, s10
	s_min_u32 s11, s11, 8
	s_andn2_b32 s7, s7, 31
	s_sub_i32 s12, s6, s7
	v_cvt_f32_ubyte0_e32 v1, s11
	v_cvt_f32_i32_e32 v0, s12
	v_rcp_iflag_f32_e32 v2, v1
	s_ashr_i32 s6, s12, 30
	s_or_b32 s13, s6, 1
	v_mul_f32_e32 v2, v0, v2
	v_trunc_f32_e32 v2, v2
	v_fma_f32 v0, -v2, v1, v0
	v_cvt_i32_f32_e32 v2, v2
	v_cmp_ge_f32_e64 s[6:7], |v0|, v1
	s_and_b64 s[6:7], s[6:7], exec
	s_cselect_b32 s6, s13, 0
	v_readfirstlane_b32 s7, v2
	s_add_i32 s6, s7, s6
	s_sext_i32_i8 s16, s6
	s_mul_i32 s6, s6, s11
	s_sub_i32 s6, s12, s6
	s_sext_i32_i8 s6, s6
	s_add_i32 s90, s10, s6

;     __device__ bool next(int i, Unit& u) const {
;         const long L = (long)i * G + c; if (L >= nwg) return false;
;         int wgid = (int)L; { const int q = nwg / NXCD, r = nwg % NXCD, xcd = wgid % NXCD, off = wgid / NXCD; wgid = (xcd < r ? xcd * (q + 1) : r * (q + 1) + (xcd - r) * q) + off; }
;         const int nig = WGM * nN, gid = wgid / nig, fm = gid * WGM, gsz = (nM - fm) < WGM ? (nM - fm) : WGM;
;         u.pm = fm + ((wgid % nig) % gsz); u.pn = (wgid % nig) / gsz; u.ko = 0; return true;
.LBB0_952:
	s_add_i32 s33, s33, 1
	s_mul_i32 s2, s33, s69
	s_mul_hi_u32 s3, s33, s8
	s_add_i32 s3, s3, s2
	s_mul_i32 s2, s33, s8
	s_add_u32 s86, s2, s9
	s_addc_u32 s87, s3, s72
	v_cmp_gt_i64_e32 vcc, s[86:87], v[204:205]
	v_cmp_lt_i64_e64 s[2:3], s[86:87], v[202:203]
	s_cbranch_vccnz .LBB0_954
	s_ashr_i32 s4, s86, 31
	s_lshr_b32 s4, s4, 29
	s_add_i32 s4, s86, s4
	s_ashr_i32 s5, s4, 3
	s_and_b32 s4, s4, -8
	s_sub_i32 s4, s86, s4
	s_cmp_lt_i32 s4, 0
	s_movk_i32 s20, 0x80
	s_cselect_b32 s20, s20, 0x80
	s_mul_i32 s4, s4, s20
	s_add_i32 s4, s4, s5
	s_cmpk_lt_i32 s86, 0x400
	s_cselect_b32 s4, s4, s86
	s_ashr_i32 s5, s4, 31
	s_lshr_b32 s5, s5, 27
	s_add_i32 s5, s4, s5
	s_ashr_i32 s20, s5, 5
	s_lshl_b32 s20, s20, 3
	s_sub_i32 s21, 0x104, s20
	s_min_i32 s21, s21, 8
	s_abs_i32 s22, s21
	v_cvt_f32_u32_e32 v0, s22
	s_sub_i32 s24, 0, s22
	s_andn2_b32 s5, s5, 31
	s_sub_i32 s5, s4, s5
	v_rcp_iflag_f32_e32 v0, v0
	s_abs_i32 s4, s5
	s_xor_b32 s23, s5, s21
	s_ashr_i32 s23, s23, 31
	v_mul_f32_e32 v0, 0x4f7ffffe, v0
	v_cvt_u32_f32_e32 v0, v0
	s_nop 0
	v_readfirstlane_b32 s25, v0
	s_mul_i32 s24, s24, s25
	s_mul_hi_u32 s24, s25, s24
	s_add_i32 s25, s25, s24
	s_mul_hi_u32 s24, s4, s25
	s_mul_i32 s25, s24, s22
	s_sub_i32 s4, s4, s25
	s_add_i32 s73, s24, 1
	s_sub_i32 s25, s4, s22
	s_cmp_ge_u32 s4, s22
	s_cselect_b32 s24, s73, s24
	s_cselect_b32 s4, s25, s4
	s_add_i32 s25, s24, 1
	s_cmp_ge_u32 s4, s22
	s_cselect_b32 s4, s25, s24
	s_xor_b32 s4, s4, s23
	s_sub_i32 s4, s4, s23
	s_mul_i32 s21, s4, s21
	s_sub_i32 s5, s5, s21
	s_add_i32 s84, s20, s5

;     __device__ bool next(int i, Unit& u) const {
;         const long L = (long)i * G + c; if (L >= nwg) return false;
;         int wgid = (int)L; { const int q = nwg / NXCD, r = nwg % NXCD, xcd = wgid % NXCD, off = wgid / NXCD; wgid = (xcd < r ? xcd * (q + 1) : r * (q + 1) + (xcd - r) * q) + off; }
;         const int nig = WGM * nN, gid = wgid / nig, fm = gid * WGM, gsz = (nM - fm) < WGM ? (nM - fm) : WGM;
; template <class Epi, bool SP2, class Sched>
; __device__ __forceinline__ void gemm_phase(LAS unsigned char* lds, const Gemm g, const Sched& S, const Epi& E) {
;     ...
;     const int wid = __builtin_amdgcn_readfirstlane(tid >> 6), lane = tid & 63, wr = wid >> 2, wc = wid & 3, fr = lane & 15, fq = lane >> 4;
;     const int K = g.K, nt = K / BK;
;     unsigned voffA[2], voffB[2];
; #pragma unroll
;     for (int i = 0; i < 2; ++i) { int R, C; stage_rc(tid * 16 + i * 8192, R, C); const int Rb = Epi::PERM ? ((R & ~31) + perm32(R & 31)) : R;
;         voffA[i] = (unsigned)(R * g.lda + C) * 2u; voffB[i] = (unsigned)(Rb * g.ldb + C) * 2u; }
;     const size_t kstep = (size_t)(BK * 2);
;     const size_t hstep = (size_t)HALF * g.lda * 2, hstepB = (size_t)HALF * g.ldb * 2;
;     const size_t tstep = 2 * hstep, tstepB = 2 * hstepB;
;     const unsigned ldsw = (unsigned)wid * 1024u;
;     const int aoff = lds_byte(wr * 64 + fr, fq * 8), boff = lds_byte(wc * 32 + fr, fq * 8);
;     ...
;     Unit cur, nxt; int ui = 0;
;     if (!S.next(0, cur)) return;
;     f32x4 acc[2][2][4][2];
; #pragma unroll
;     for (int a = 0; a < 2; ++a)
; #pragma unroll
;         for (int b = 0; b < 2; ++b)
; #pragma unroll
;             for (int m = 0; m < 4; ++m)
; #pragma unroll
;                 for (int n = 0; n < 2; ++n) acc[a][b][m][n] = (f32x4){0.f, 0.f, 0.f, 0.f};
;     bf16x8 At[4][2], B0[2][2], B1[2][2];
;     const char* cA = (const char*)g.A + (size_t)cur.pm * tstep + cur.ko; const char* cB = (const char*)g.Bt + (size_t)cur.pn * tstepB + cur.ko;
;     if constexpr (SP2) {
;         PG8_STAGE(PG8_SB(0, 0), cB, voffB); PG8_STAGE(PG8_SB(0, 1), cB + hstepB, voffB); PG8_STAGE(PG8_SA(0, 0), cA, voffA); PG8_STAGE(PG8_SA(0, 1), cA + hstep, voffA);
;         if (wr == 1) PG8_BAR;
;         PG8_WAIT_V(2); PG8_BAR;
;         PG8_STAGE(PG8_SB(1, 0), cB + kstep, voffB); PG8_STAGE(PG8_SA(1, 0), cA + kstep, voffA); PG8_STAGE(PG8_SB(1, 1), cB + hstepB + kstep, voffB);
;         PG8_WAIT_V(6); PG8_BAR;
.LBB0_1030:
	s_or_b64 exec, exec, s[0:1]
	s_mov_b64 s[0:1], s[74:75]
	s_mov_b32 s62, s83
	s_mov_b32 s12, s14
	s_mov_b32 s64, s18
	v_mov_b32_e32 v14, v242
	s_waitcnt lgkmcnt(0)
	s_barrier
	s_cmpk_lt_i32 s62, 0x1040
	s_nop 0
	v_readfirstlane_b32 s7, v14
	s_cbranch_scc0 .LBB0_1046
	v_lshlrev_b32_e32 v0, 4, v14
	v_add_u32_e32 v1, 0x2000, v0
	v_ashrrev_i32_e32 v2, 31, v1
	v_lshrrev_b32_e32 v2, 22, v2
	v_add_u32_e32 v2, v1, v2
	v_ashrrev_i32_e32 v8, 10, v2
	v_mul_i32_i24_e32 v2, 0x400, v8
	v_sub_u32_e32 v1, v1, v2
	v_lshrrev_b32_e32 v2, 4, v1
	s_mul_i32 s3, s12, 0x1f00000
	v_bitop3_b32 v1, v2, v1, 32 bitop3:0x6c
	s_mul_hi_i32 s2, s12, 0x1f00000
	s_add_u32 s3, s0, s3
	v_ashrrev_i32_e32 v2, 31, v1
	s_addc_u32 s2, s1, s2
	v_lshrrev_b32_e32 v2, 26, v2
	s_add_u32 s65, s0, 0x4200000
	v_add_u32_e32 v2, v1, v2
	v_lshlrev_b32_e32 v3, 3, v8
	s_addc_u32 s68, s1, 0
	v_ashrrev_i32_e32 v9, 6, v2
	v_and_b32_e32 v3, -16, v3
	s_add_u32 s69, s3, 0x1280000
	v_add_u32_e32 v3, v9, v3
	s_addc_u32 s72, s2, 0
	v_and_b32_e32 v4, 3, v9
	s_mov_b32 s2, 0x1fffe0
	v_lshrrev_b32_e32 v5, 2, v3
	v_lshlrev_b32_e32 v6, 1, v3
	v_and_b32_e32 v2, 0xc0, v2
	v_and_or_b32 v4, v3, s2, v4
	v_and_b32_e32 v5, 4, v5
	v_and_b32_e32 v6, 24, v6
	v_sub_u32_e32 v1, v1, v2
	v_or3_b32 v4, v4, v5, v6
	v_lshlrev_b32_e32 v5, 5, v8
	v_ashrrev_i16_sdwa v1, v244, sext(v1) dst_sel:DWORD dst_unused:UNUSED_PAD src0_sel:DWORD src1_sel:BYTE_0
	v_and_b32_e32 v5, 32, v5
	v_bfe_i32 v10, v1, 0, 16
	v_add_lshl_u32 v1, v5, v10, 1
	v_lshl_add_u32 v130, v4, 11, v1
	v_lshl_add_u32 v132, v3, 11, v1
	v_bfe_i32 v1, v14, 27, 1
	v_lshrrev_b32_e32 v1, 22, v1
	v_add_u32_e32 v1, v0, v1
	v_and_b32_e32 v1, 0xfffffc00, v1
	v_sub_u32_e32 v0, v0, v1
	v_lshrrev_b32_e32 v1, 4, v0
	v_ashrrev_i32_e32 v2, 31, v14
	v_bitop3_b32 v0, v1, v0, 32 bitop3:0x6c
	v_lshrrev_b32_e32 v2, 26, v2
	v_ashrrev_i32_e32 v1, 31, v0
	v_add_u32_e32 v2, v14, v2
	v_lshrrev_b32_e32 v1, 26, v1
	v_ashrrev_i32_e32 v12, 6, v2
	v_add_u32_e32 v1, v0, v1
	v_lshlrev_b32_e32 v2, 3, v12
	v_ashrrev_i32_e32 v11, 6, v1
	v_and_b32_e32 v2, -16, v2
	s_ashr_i32 s73, s62, 31
	v_add_u32_e32 v2, v11, v2
	v_and_b32_e32 v3, 3, v11
	v_and_or_b32 v3, v2, s2, v3
	s_lshr_b32 s2, s73, 29
	s_add_i32 s2, s62, s2
	s_ashr_i32 s8, s7, 6
	s_ashr_i32 s3, s2, 3
	s_and_b32 s2, s2, -8
	s_ashr_i32 s9, s7, 8
	s_lshl_b32 s79, s8, 10
	s_sub_i32 s2, s62, s2
	s_cmp_lt_i32 s2, 0
	s_movk_i32 s4, 0x200
	s_cselect_b32 s4, s4, 0x200
	s_mul_i32 s2, s2, s4
	s_add_i32 s2, s2, s3
	s_ashr_i32 s3, s2, 31
	s_lshr_b32 s3, s3, 25
	v_lshrrev_b32_e32 v4, 2, v2
	v_lshlrev_b32_e32 v5, 1, v2
	v_and_b32_e32 v1, 0xc0, v1
	s_add_i32 s3, s2, s3
	v_and_b32_e32 v4, 4, v4
	v_and_b32_e32 v5, 24, v5
	v_sub_u32_e32 v0, v0, v1
	s_ashr_i32 s4, s3, 7
	v_or3_b32 v3, v3, v4, v5
	v_lshlrev_b32_e32 v4, 5, v12
	v_ashrrev_i16_sdwa v0, v244, sext(v0) dst_sel:DWORD dst_unused:UNUSED_PAD src0_sel:DWORD src1_sel:BYTE_0
	s_lshl_b32 s4, s4, 3
	v_and_b32_e32 v4, 32, v4
	v_bfe_i32 v13, v0, 0, 16
	s_sub_i32 s5, 0x104, s4
	v_add_lshl_u32 v0, v4, v13, 1
	s_min_u32 s5, s5, 8
	s_and_b32 s3, s3, 0xffffff80
	v_lshl_add_u32 v64, v3, 11, v0
	s_sub_i32 s10, s2, s3
	v_cvt_f32_ubyte0_e32 v3, s5
	v_cvt_f32_i32_e32 v1, s10
	v_rcp_iflag_f32_e32 v4, v3
	s_waitcnt vmcnt(0)
	v_lshl_add_u32 v134, v2, 11, v0
	s_ashr_i32 s2, s10, 30
	s_or_b32 s6, s2, 1
	v_mul_f32_e32 v0, v1, v4
	v_trunc_f32_e32 v0, v0
	v_fma_f32 v1, -v0, v3, v1
	v_cvt_i32_f32_e32 v0, v0
	v_cmp_ge_f32_e64 s[2:3], |v1|, v3
	s_and_b64 s[2:3], s[2:3], exec
	s_cselect_b32 s2, s6, 0
	v_readfirstlane_b32 s3, v0
	s_add_i32 s6, s3, s2
	s_mul_i32 s2, s6, s5
	s_sub_i32 s2, s10, s2
	s_sext_i32_i8 s2, s2
	s_add_i32 s4, s4, s2
	s_ashr_i32 s5, s4, 31
	s_bfe_i64 s[10:11], s[6:7], 0x80000
	s_lshl_b64 s[2:3], s[4:5], 19
	s_lshl_b64 s[10:11], s[10:11], 19
	s_add_u32 s10, s69, s10
	s_addc_u32 s11, s72, s11
	s_add_i32 s83, s79, 0
	s_add_i32 m0, s83, 0x10000
	v_mov_b32_e32 v131, v65
	global_load_lds_dwordx4 v64, s[10:11]
	s_add_i32 m0, s83, 0x12000
	s_add_u32 s14, s10, 0x40000
	global_load_lds_dwordx4 v130, s[10:11]
	s_addc_u32 s15, s11, 0
	s_add_i32 m0, s83, 0x14000
	v_mov_b32_e32 v135, v65
	global_load_lds_dwordx4 v64, s[14:15]
	s_add_i32 m0, s83, 0x16000
	s_add_u32 s16, s65, s2
	s_addc_u32 s17, s68, s3
	s_add_i32 s90, s83, 0x2000
	global_load_lds_dwordx4 v130, s[14:15]
	s_mov_b32 m0, s83
	s_add_u32 s2, s16, 0x40000
	global_load_lds_dwordx4 v134, s[16:17]
	s_mov_b32 m0, s90
	s_addc_u32 s3, s17, 0
	s_add_i32 s91, s83, 0x4000
	global_load_lds_dwordx4 v132, s[16:17]
	s_mov_b32 m0, s91
	s_add_i32 s92, s83, 0x6000
	global_load_lds_dwordx4 v134, s[2:3]
	s_mov_b32 m0, s92
	v_mov_b32_e32 v133, v65
	global_load_lds_dwordx4 v132, s[2:3]
	s_cmp_eq_u32 s9, 1
	v_lshl_add_u64 v[6:7], s[10:11], 0, v[64:65]
	v_lshl_add_u64 v[4:5], s[10:11], 0, v[130:131]
	v_lshl_add_u64 v[0:1], s[16:17], 0, v[134:135]
	s_cselect_b64 s[2:3], -1, 0
	s_cmp_lg_u32 s9, 1
	v_lshl_add_u64 v[2:3], s[16:17], 0, v[132:133]
	s_cbranch_scc1 .LBB0_1033
	s_barrier

;     __device__ bool next(int i, Unit& u) const {
;         const long L = (long)i * G + c; if (L >= nwg) return false;
;         int wgid = (int)L; { const int q = nwg / NXCD, r = nwg % NXCD, xcd = wgid % NXCD, off = wgid / NXCD; wgid = (xcd < r ? xcd * (q + 1) : r * (q + 1) + (xcd - r) * q) + off; }
;         const int nig = WGM * nN, gid = wgid / nig, fm = gid * WGM, gsz = (nM - fm) < WGM ? (nM - fm) : WGM;
;         u.pm = fm + ((wgid % nig) % gsz); u.pn = (wgid % nig) / gsz; u.ko = 0; return true;
.LBB0_1036:
	s_add_i32 s96, s96, 1
	s_mul_i32 s0, s96, s93
	s_mul_hi_u32 s1, s96, s64
	s_add_i32 s1, s1, s0
	s_mul_i32 s0, s96, s64
	s_add_u32 s6, s0, s62
	s_addc_u32 s7, s1, s73
	v_cmp_gt_i64_e32 vcc, s[6:7], v[208:209]
	v_cmp_lt_i64_e64 s[0:1], s[6:7], v[206:207]
	s_cbranch_vccnz .LBB0_1038
	s_ashr_i32 s7, s6, 31
	s_lshr_b32 s7, s7, 29
	s_add_i32 s7, s6, s7
	s_ashr_i32 s8, s7, 3
	s_and_b32 s7, s7, -8
	s_sub_i32 s6, s6, s7
	s_cmp_lt_i32 s6, 0
	s_movk_i32 s7, 0x200
	s_cselect_b32 s7, s7, 0x200
	s_mul_i32 s6, s6, s7
	s_add_i32 s6, s6, s8
	s_mul_i32 s7, s96, s64
	s_add_i32 s7, s7, s62
	s_cmpk_lt_i32 s7, 0x1000
	s_cselect_b32 s6, s6, s7
	s_ashr_i32 s7, s6, 31
	s_lshr_b32 s7, s7, 25
	s_add_i32 s7, s6, s7
	s_ashr_i32 s8, s7, 7
	s_lshl_b32 s8, s8, 3
	s_sub_i32 s9, 0x104, s8
	s_min_i32 s9, s9, 8
	s_abs_i32 s12, s9
	v_cvt_f32_u32_e32 v0, s12
	s_sub_i32 s14, 0, s12
	s_and_b32 s7, s7, 0xffffff80
	s_sub_i32 s6, s6, s7
	v_rcp_iflag_f32_e32 v0, v0
	s_abs_i32 s7, s6
	s_xor_b32 s13, s6, s9
	s_ashr_i32 s13, s13, 31
	v_mul_f32_e32 v0, 0x4f7ffffe, v0
	v_cvt_u32_f32_e32 v0, v0
	s_nop 0
	v_readfirstlane_b32 s15, v0
	s_mul_i32 s14, s14, s15
	s_mul_hi_u32 s14, s15, s14
	s_add_i32 s15, s15, s14
	s_mul_hi_u32 s14, s7, s15
	s_mul_i32 s15, s14, s12
	s_sub_i32 s7, s7, s15
	s_add_i32 s18, s14, 1
	s_sub_i32 s15, s7, s12
	s_cmp_ge_u32 s7, s12
	s_cselect_b32 s14, s18, s14
	s_cselect_b32 s7, s15, s7
	s_add_i32 s15, s14, 1
	s_cmp_ge_u32 s7, s12
	s_cselect_b32 s7, s15, s14
	s_xor_b32 s7, s7, s13
	s_sub_i32 s60, s7, s13
	s_mul_i32 s7, s60, s9
	s_sub_i32 s6, s6, s7
	s_add_i32 s84, s8, s6
